# v82 + residual GEMM K-loop: all 16 LDS-DMA loads per iteration use SGPR base + 32-bit lane offset (saddr form); the 16 v_lshl_add_u64 address adds per iteration removed
# speedup vs baseline: 1.0062x; 1.0017x over previous
; #define PG8_STAGE(bufoff, gbase, voff) do { _Pragma("unroll") for (int _i = 0; _i < 2; ++_i) \
;         __builtin_amdgcn_global_load_lds((const unsigned*)((const char*)(gbase) + (voff)[_i]), (PG8_LAS unsigned*)(lds + (bufoff) + ldsw + _i * 8192), 16, 0, 0); } while (0)
; #define PG8_LDA(dst, b, h) do { _Pragma("unroll") for (int m = 0; m < 4; ++m) _Pragma("unroll") for (int k = 0; k < 2; ++k) dst[m][k] = *(const PG8_LAS bf16x8*)(lds + PG8_SA(b, h) + aoff + m * 2048 + k * 1024); } while (0)
; #define PG8_LDB(dst, b, h) do { _Pragma("unroll") for (int n = 0; n < 2; ++n) _Pragma("unroll") for (int k = 0; k < 2; ++k) dst[n][k] = *(const PG8_LAS bf16x8*)(lds + PG8_SB(b, h) + boff + n * 2048 + k * 1024); } while (0)
; #define PG8_MMA(ai, bj, At, Bt) do { __builtin_amdgcn_s_setprio(1); _Pragma("unroll") for (int m = 0; m < 4; ++m) _Pragma("unroll") for (int n = 0; n < 2; ++n) _Pragma("unroll") for (int k = 0; k < 2; ++k) \
;         acc[ai][bj][m][n] = mma16<Epi::I8>(Bt[n][k], At[m][k], acc[ai][bj][m][n]); __builtin_amdgcn_s_setprio(0); } while (0)
; #define PG8_WAIT_V(n) asm volatile("s_waitcnt vmcnt(" #n ")" ::: "memory")
; #define PG8_WAIT_L(n) asm volatile("s_waitcnt lgkmcnt(" #n ")" ::: "memory")
; #define PG8_BAR __builtin_amdgcn_s_barrier()
; template <class Epi, class Sched, bool ALIGN_EPI = false, bool SP2 = false>
; __device__ __forceinline__ void gemm_phase(PG8_LAS unsigned char* lds, const Gemm g, const Sched& S, const Epi& E) {
;     ...
;             const bool last = (t == nt - 2);
;             const char* a1 = cA + (size_t)(t + 1) * kstep;
;             const char* a2 = last ? nA : cA + (size_t)(t + 2) * kstep; const char* b2 = last ? nB : cB + (size_t)(t + 2) * kstep;
;             const char* a3 = a2 + kstep; const char* b3 = b2 + kstep;
;             if (last && has_next) S.a_ready(nxt);
;             if constexpr (SP2) {
;             PG8_LDB(B0, 0, 0); PG8_LDB(B1, 0, 1); PG8_SCHED; PG8_LDA(At, 0, 0); PG8_STAGE(PG8_SA(1, 1), a1 + hstep, voffA);
;             PG8_WAIT_V(8); PG8_WAIT_L(0); PG8_BAR; PG8_MMA(0, 0, At, B0); PG8_MMA(0, 1, At, B1); PG8_BAR; PG8_SCHED;
;             PG8_LDA(At, 0, 1); PG8_STAGE(PG8_SB(0, 0), b2, voffB); PG8_STAGE(PG8_SB(0, 1), b2 + hstep, voffB); PG8_STAGE(PG8_SA(0, 0), a2, voffA);
;             PG8_WAIT_V(8); PG8_WAIT_L(0); PG8_BAR; PG8_MMA(1, 0, At, B0); PG8_MMA(1, 1, At, B1); PG8_BAR; PG8_SCHED;
.Lpeel175:
	s_add_i32 vcc_lo, s8, 2
	s_add_u32 s4, s6, s98
	s_addc_u32 s5, s7, 0
	s_add_i32 vcc_hi, 0, 0x10000
	s_cmp_eq_u32 s13, s8
	s_cselect_b32 s9, s1, s5
	s_cselect_b32 s8, s0, s4
	s_cselect_b32 s5, s97, s85
	s_cselect_b32 s4, s96, s67
	s_add_i32 s84, 0, 0x14000
	v_add_u32_e32 v122, vcc_hi, v248
	v_add_u32_e32 v154, s84, v248
	ds_read_b128 v[98:101], v122
	ds_read_b128 v[102:105], v122 offset:1024
	ds_read_b128 v[114:117], v122 offset:2048
	ds_read_b128 v[122:125], v122 offset:3072
	ds_read_b128 v[130:133], v154
	ds_read_b128 v[138:141], v154 offset:1024
	ds_read_b128 v[146:149], v154 offset:2048
	ds_read_b128 v[154:157], v154 offset:3072
	s_add_i32 m0, s81, 0xc000
	ds_read_b128 v[162:165], v249
	ds_read_b128 v[166:169], v249 offset:1024
	ds_read_b128 v[170:173], v249 offset:2048
	ds_read_b128 v[174:177], v249 offset:3072
	ds_read_b128 v[178:181], v249 offset:4096
	ds_read_b128 v[182:185], v249 offset:5120
	ds_read_b128 v[186:189], v249 offset:6144
	ds_read_b128 v[190:193], v249 offset:7168
	global_load_lds_dwordx4 v200, s[6:7]
	s_add_i32 m0, s81, 0xe000
	s_nop 0
	global_load_lds_dwordx4 v210, s[6:7]
	s_waitcnt vmcnt(8)
	s_waitcnt lgkmcnt(0)
	s_barrier
	s_waitcnt lgkmcnt(0)
	v_mfma_f32_16x16x32_bf16 v[158:161], v[98:101], v[162:165], 0
	v_mfma_f32_16x16x32_bf16 v[150:153], v[114:117], v[162:165], 0
	v_mfma_f32_16x16x32_bf16 v[118:121], v[114:117], v[170:173], 0
	v_mfma_f32_16x16x32_bf16 v[126:129], v[98:101], v[170:173], 0
	v_mfma_f32_16x16x32_bf16 v[94:97], v[98:101], v[178:181], 0
	v_mfma_f32_16x16x32_bf16 v[90:93], v[114:117], v[178:181], 0
	v_mfma_f32_16x16x32_bf16 v[74:77], v[114:117], v[186:189], 0
	v_mfma_f32_16x16x32_bf16 v[78:81], v[98:101], v[186:189], 0
	v_mfma_f32_16x16x32_bf16 v[158:161], v[102:105], v[166:169], v[158:161]
	v_mfma_f32_16x16x32_bf16 v[150:153], v[122:125], v[166:169], v[150:153]
	v_mfma_f32_16x16x32_bf16 v[118:121], v[122:125], v[174:177], v[118:121]
	v_mfma_f32_16x16x32_bf16 v[126:129], v[102:105], v[174:177], v[126:129]
	v_mfma_f32_16x16x32_bf16 v[94:97], v[102:105], v[182:185], v[94:97]
	v_mfma_f32_16x16x32_bf16 v[90:93], v[122:125], v[182:185], v[90:93]
	v_mfma_f32_16x16x32_bf16 v[74:77], v[122:125], v[190:193], v[74:77]
	v_mfma_f32_16x16x32_bf16 v[78:81], v[102:105], v[190:193], v[78:81]
	v_mfma_f32_16x16x32_bf16 v[142:145], v[130:133], v[162:165], 0
	v_mfma_f32_16x16x32_bf16 v[134:137], v[146:149], v[162:165], 0
	v_mfma_f32_16x16x32_bf16 v[106:109], v[146:149], v[170:173], 0
	v_mfma_f32_16x16x32_bf16 v[110:113], v[130:133], v[170:173], 0
	v_mfma_f32_16x16x32_bf16 v[86:89], v[130:133], v[178:181], 0
	v_mfma_f32_16x16x32_bf16 v[82:85], v[146:149], v[178:181], 0
	v_mfma_f32_16x16x32_bf16 v[66:69], v[146:149], v[186:189], 0
	v_mfma_f32_16x16x32_bf16 v[70:73], v[130:133], v[186:189], 0
	v_mfma_f32_16x16x32_bf16 v[142:145], v[138:141], v[166:169], v[142:145]
	v_mfma_f32_16x16x32_bf16 v[134:137], v[154:157], v[166:169], v[134:137]
	v_mfma_f32_16x16x32_bf16 v[106:109], v[154:157], v[174:177], v[106:109]
	v_mfma_f32_16x16x32_bf16 v[110:113], v[138:141], v[174:177], v[110:113]
	v_mfma_f32_16x16x32_bf16 v[86:89], v[138:141], v[182:185], v[86:89]
	v_mfma_f32_16x16x32_bf16 v[82:85], v[154:157], v[182:185], v[82:85]
	v_mfma_f32_16x16x32_bf16 v[66:69], v[154:157], v[190:193], v[66:69]
	v_mfma_f32_16x16x32_bf16 v[70:73], v[138:141], v[190:193], v[70:73]
	s_barrier
	s_add_i32 vcc_hi, vcc_hi, s80
	s_mov_b64 s[92:93], s[4:5]
	s_mov_b32 m0, vcc_hi
	ds_read_b128 v[162:165], v249 offset:16384
	ds_read_b128 v[166:169], v249 offset:17408
	ds_read_b128 v[170:173], v249 offset:18432
	ds_read_b128 v[174:177], v249 offset:19456
	ds_read_b128 v[178:181], v249 offset:20480
	ds_read_b128 v[182:185], v249 offset:21504
	ds_read_b128 v[186:189], v249 offset:22528
	ds_read_b128 v[190:193], v249 offset:23552
	global_load_lds_dwordx4 v0, s[4:5]
	s_add_i32 m0, vcc_hi, 0x2000
	s_add_i32 s84, s84, s80
	global_load_lds_dwordx4 v198, s[4:5]
	s_add_u32 s4, s4, s100
	s_addc_u32 s5, s5, 0
	s_mov_b32 m0, s84
	s_nop 0
	global_load_lds_dwordx4 v0, s[4:5]
	s_add_i32 m0, s84, 0x2000
	s_nop 0
	global_load_lds_dwordx4 v198, s[4:5]
	s_mov_b32 m0, s81
	s_nop 0
	global_load_lds_dwordx4 v194, s[8:9]
	s_mov_b32 m0, s70
	s_nop 0
	global_load_lds_dwordx4 v196, s[8:9]
	s_waitcnt vmcnt(8)
	s_waitcnt lgkmcnt(0)
	s_barrier
	s_waitcnt lgkmcnt(0)
	v_mfma_f32_16x16x32_bf16 v[62:65], v[98:101], v[162:165], 0
	v_mfma_f32_16x16x32_bf16 v[58:61], v[114:117], v[162:165], 0
	v_mfma_f32_16x16x32_bf16 v[42:45], v[114:117], v[170:173], 0
	v_mfma_f32_16x16x32_bf16 v[46:49], v[98:101], v[170:173], 0
	v_mfma_f32_16x16x32_bf16 v[30:33], v[98:101], v[178:181], 0
	v_mfma_f32_16x16x32_bf16 v[26:29], v[114:117], v[178:181], 0
	v_mfma_f32_16x16x32_bf16 v[10:13], v[114:117], v[186:189], 0
	v_mfma_f32_16x16x32_bf16 v[14:17], v[98:101], v[186:189], 0
	v_mfma_f32_16x16x32_bf16 v[62:65], v[102:105], v[166:169], v[62:65]
	v_mfma_f32_16x16x32_bf16 v[58:61], v[122:125], v[166:169], v[58:61]
	v_mfma_f32_16x16x32_bf16 v[42:45], v[122:125], v[174:177], v[42:45]
	v_mfma_f32_16x16x32_bf16 v[46:49], v[102:105], v[174:177], v[46:49]
	v_mfma_f32_16x16x32_bf16 v[30:33], v[102:105], v[182:185], v[30:33]
	v_mfma_f32_16x16x32_bf16 v[26:29], v[122:125], v[182:185], v[26:29]
	v_mfma_f32_16x16x32_bf16 v[10:13], v[122:125], v[190:193], v[10:13]
	v_mfma_f32_16x16x32_bf16 v[14:17], v[102:105], v[190:193], v[14:17]
	v_mfma_f32_16x16x32_bf16 v[54:57], v[130:133], v[162:165], 0
	v_mfma_f32_16x16x32_bf16 v[50:53], v[146:149], v[162:165], 0
	v_mfma_f32_16x16x32_bf16 v[34:37], v[146:149], v[170:173], 0
	v_mfma_f32_16x16x32_bf16 v[38:41], v[130:133], v[170:173], 0
	v_mfma_f32_16x16x32_bf16 v[22:25], v[130:133], v[178:181], 0
	v_mfma_f32_16x16x32_bf16 v[18:21], v[146:149], v[178:181], 0
	v_mfma_f32_16x16x32_bf16 v[2:5], v[146:149], v[186:189], 0
	v_mfma_f32_16x16x32_bf16 v[6:9], v[130:133], v[186:189], 0
	v_mfma_f32_16x16x32_bf16 v[54:57], v[138:141], v[166:169], v[54:57]
	v_mfma_f32_16x16x32_bf16 v[50:53], v[154:157], v[166:169], v[50:53]
	v_mfma_f32_16x16x32_bf16 v[34:37], v[154:157], v[174:177], v[34:37]
	v_mfma_f32_16x16x32_bf16 v[38:41], v[138:141], v[174:177], v[38:41]
	v_mfma_f32_16x16x32_bf16 v[22:25], v[138:141], v[182:185], v[22:25]
	v_mfma_f32_16x16x32_bf16 v[18:21], v[154:157], v[182:185], v[18:21]
	v_mfma_f32_16x16x32_bf16 v[2:5], v[154:157], v[190:193], v[2:5]
	v_mfma_f32_16x16x32_bf16 v[6:9], v[138:141], v[190:193], v[6:9]
	s_barrier
; #define PG8_STAGE(bufoff, gbase, voff) do { _Pragma("unroll") for (int _i = 0; _i < 2; ++_i) \
;         __builtin_amdgcn_global_load_lds((const unsigned*)((const char*)(gbase) + (voff)[_i]), (PG8_LAS unsigned*)(lds + (bufoff) + ldsw + _i * 8192), 16, 0, 0); } while (0)
; #define PG8_LDA(dst, b, h) do { _Pragma("unroll") for (int m = 0; m < 4; ++m) _Pragma("unroll") for (int k = 0; k < 2; ++k) dst[m][k] = *(const PG8_LAS bf16x8*)(lds + PG8_SA(b, h) + aoff + m * 2048 + k * 1024); } while (0)
; #define PG8_LDB(dst, b, h) do { _Pragma("unroll") for (int n = 0; n < 2; ++n) _Pragma("unroll") for (int k = 0; k < 2; ++k) dst[n][k] = *(const PG8_LAS bf16x8*)(lds + PG8_SB(b, h) + boff + n * 2048 + k * 1024); } while (0)
; #define PG8_MMA(ai, bj, At, Bt) do { __builtin_amdgcn_s_setprio(1); _Pragma("unroll") for (int m = 0; m < 4; ++m) _Pragma("unroll") for (int n = 0; n < 2; ++n) _Pragma("unroll") for (int k = 0; k < 2; ++k) \
;         acc[ai][bj][m][n] = mma16<Epi::I8>(Bt[n][k], At[m][k], acc[ai][bj][m][n]); __builtin_amdgcn_s_setprio(0); } while (0)
; #define PG8_WAIT_V(n) asm volatile("s_waitcnt vmcnt(" #n ")" ::: "memory")
; #define PG8_WAIT_L(n) asm volatile("s_waitcnt lgkmcnt(" #n ")" ::: "memory")
; #define PG8_BAR __builtin_amdgcn_s_barrier()
; #define PG8_SCHED __builtin_amdgcn_sched_barrier(0)
; template <class Epi, class Sched, bool ALIGN_EPI = false, bool SP2 = false>
; __device__ __forceinline__ void gemm_phase(PG8_LAS unsigned char* lds, const Gemm g, const Sched& S, const Epi& E) {
;     ...
;         for (int t = 0; t < nt; t += 2) {
;     ...
;             PG8_LDB(B0, 1, 0); PG8_LDB(B1, 1, 1); PG8_SCHED; PG8_LDA(At, 1, 0); PG8_STAGE(PG8_SA(0, 1), a2 + hstep, voffA);
;             PG8_WAIT_V(8); PG8_WAIT_L(0); PG8_BAR; PG8_MMA(0, 0, At, B0); PG8_MMA(0, 1, At, B1); PG8_BAR; PG8_SCHED;
;             PG8_LDA(At, 1, 1); PG8_STAGE(PG8_SB(1, 0), b3, voffB); PG8_STAGE(PG8_SB(1, 1), b3 + hstep, voffB); PG8_STAGE(PG8_SA(1, 0), a3, voffA);
;             PG8_WAIT_V(8); PG8_WAIT_L(0); PG8_BAR; PG8_MMA(1, 0, At, B0); PG8_MMA(1, 1, At, B1); PG8_BAR; PG8_SCHED;
	s_add_i32 s84, 0, 0x18000
	s_add_i32 vcc_hi, 0, 0x1c000
	v_add_u32_e32 v122, s84, v248
	v_add_u32_e32 v154, vcc_hi, v248
	ds_read_b128 v[98:101], v122
	ds_read_b128 v[102:105], v122 offset:1024
	ds_read_b128 v[114:117], v122 offset:2048
	ds_read_b128 v[122:125], v122 offset:3072
	ds_read_b128 v[130:133], v154
	ds_read_b128 v[138:141], v154 offset:1024
	ds_read_b128 v[146:149], v154 offset:2048
	ds_read_b128 v[154:157], v154 offset:3072
	s_add_u32 s4, s8, s100
	s_addc_u32 s5, s9, 0
	s_mov_b32 m0, s71
	ds_read_b128 v[162:165], v249 offset:32768
	ds_read_b128 v[166:169], v249 offset:33792
	ds_read_b128 v[170:173], v249 offset:34816
	ds_read_b128 v[174:177], v249 offset:35840
	ds_read_b128 v[178:181], v249 offset:36864
	ds_read_b128 v[182:185], v249 offset:37888
	ds_read_b128 v[186:189], v249 offset:38912
	ds_read_b128 v[190:193], v249 offset:39936
	global_load_lds_dwordx4 v194, s[4:5]
	s_mov_b32 m0, s12
	s_nop 0
	global_load_lds_dwordx4 v196, s[4:5]
	s_waitcnt vmcnt(8)
	s_waitcnt lgkmcnt(0)
	s_barrier
	s_waitcnt lgkmcnt(0)
	v_mfma_f32_16x16x32_bf16 v[158:161], v[98:101], v[162:165], v[158:161]
	v_mfma_f32_16x16x32_bf16 v[150:153], v[114:117], v[162:165], v[150:153]
	v_mfma_f32_16x16x32_bf16 v[118:121], v[114:117], v[170:173], v[118:121]
	v_mfma_f32_16x16x32_bf16 v[126:129], v[98:101], v[170:173], v[126:129]
	v_mfma_f32_16x16x32_bf16 v[94:97], v[98:101], v[178:181], v[94:97]
	v_mfma_f32_16x16x32_bf16 v[90:93], v[114:117], v[178:181], v[90:93]
	v_mfma_f32_16x16x32_bf16 v[74:77], v[114:117], v[186:189], v[74:77]
	v_mfma_f32_16x16x32_bf16 v[78:81], v[98:101], v[186:189], v[78:81]
	v_mfma_f32_16x16x32_bf16 v[158:161], v[102:105], v[166:169], v[158:161]
	v_mfma_f32_16x16x32_bf16 v[150:153], v[122:125], v[166:169], v[150:153]
	v_mfma_f32_16x16x32_bf16 v[118:121], v[122:125], v[174:177], v[118:121]
	v_mfma_f32_16x16x32_bf16 v[126:129], v[102:105], v[174:177], v[126:129]
	v_mfma_f32_16x16x32_bf16 v[94:97], v[102:105], v[182:185], v[94:97]
	v_mfma_f32_16x16x32_bf16 v[90:93], v[122:125], v[182:185], v[90:93]
	v_mfma_f32_16x16x32_bf16 v[74:77], v[122:125], v[190:193], v[74:77]
	v_mfma_f32_16x16x32_bf16 v[78:81], v[102:105], v[190:193], v[78:81]
	v_mfma_f32_16x16x32_bf16 v[142:145], v[130:133], v[162:165], v[142:145]
	v_mfma_f32_16x16x32_bf16 v[134:137], v[146:149], v[162:165], v[134:137]
	v_mfma_f32_16x16x32_bf16 v[106:109], v[146:149], v[170:173], v[106:109]
	v_mfma_f32_16x16x32_bf16 v[110:113], v[130:133], v[170:173], v[110:113]
	v_mfma_f32_16x16x32_bf16 v[86:89], v[130:133], v[178:181], v[86:89]
	v_mfma_f32_16x16x32_bf16 v[82:85], v[146:149], v[178:181], v[82:85]
	v_mfma_f32_16x16x32_bf16 v[66:69], v[146:149], v[186:189], v[66:69]
	v_mfma_f32_16x16x32_bf16 v[70:73], v[130:133], v[186:189], v[70:73]
	v_mfma_f32_16x16x32_bf16 v[142:145], v[138:141], v[166:169], v[142:145]
	v_mfma_f32_16x16x32_bf16 v[134:137], v[154:157], v[166:169], v[134:137]
	v_mfma_f32_16x16x32_bf16 v[106:109], v[154:157], v[174:177], v[106:109]
	v_mfma_f32_16x16x32_bf16 v[110:113], v[138:141], v[174:177], v[110:113]
	v_mfma_f32_16x16x32_bf16 v[86:89], v[138:141], v[182:185], v[86:89]
	v_mfma_f32_16x16x32_bf16 v[82:85], v[154:157], v[182:185], v[82:85]
	v_mfma_f32_16x16x32_bf16 v[66:69], v[154:157], v[190:193], v[66:69]
	v_mfma_f32_16x16x32_bf16 v[70:73], v[138:141], v[190:193], v[70:73]
	s_barrier
	s_add_u32 s4, s92, s98
	s_addc_u32 s5, s93, 0
	s_add_i32 m0, s84, s80
	ds_read_b128 v[162:165], v249 offset:49152
	ds_read_b128 v[166:169], v249 offset:50176
	ds_read_b128 v[170:173], v249 offset:51200
	ds_read_b128 v[174:177], v249 offset:52224
	ds_read_b128 v[178:181], v249 offset:53248
	ds_read_b128 v[182:185], v249 offset:54272
	ds_read_b128 v[186:189], v249 offset:55296
	ds_read_b128 v[190:193], v249 offset:56320
	global_load_lds_dwordx4 v0, s[4:5]
	s_add_i32 m0, s84, s80
	s_add_i32 m0, m0, 0x2000
	s_nop 0
	global_load_lds_dwordx4 v198, s[4:5]
	s_add_u32 s4, s4, s100
	s_addc_u32 s5, s5, 0
	s_add_i32 m0, vcc_hi, s80
	s_nop 0
	global_load_lds_dwordx4 v0, s[4:5]
	s_add_i32 m0, vcc_hi, s80
	s_add_i32 m0, m0, 0x2000
	s_nop 0
	global_load_lds_dwordx4 v198, s[4:5]
	s_add_u32 s4, s8, s98
	s_addc_u32 s5, s9, 0
	s_mov_b32 m0, s10
	s_nop 0
	global_load_lds_dwordx4 v194, s[4:5]
	s_mov_b32 m0, s11
	s_nop 0
	global_load_lds_dwordx4 v196, s[4:5]
	s_waitcnt vmcnt(8)
	s_waitcnt lgkmcnt(0)
	s_barrier
	s_waitcnt lgkmcnt(0)
	v_mfma_f32_16x16x32_bf16 v[62:65], v[98:101], v[162:165], v[62:65]
	v_mfma_f32_16x16x32_bf16 v[58:61], v[114:117], v[162:165], v[58:61]
	v_mfma_f32_16x16x32_bf16 v[42:45], v[114:117], v[170:173], v[42:45]
	v_mfma_f32_16x16x32_bf16 v[46:49], v[98:101], v[170:173], v[46:49]
	v_mfma_f32_16x16x32_bf16 v[30:33], v[98:101], v[178:181], v[30:33]
	v_mfma_f32_16x16x32_bf16 v[26:29], v[114:117], v[178:181], v[26:29]
	v_mfma_f32_16x16x32_bf16 v[10:13], v[114:117], v[186:189], v[10:13]
	v_mfma_f32_16x16x32_bf16 v[14:17], v[98:101], v[186:189], v[14:17]
	v_mfma_f32_16x16x32_bf16 v[62:65], v[102:105], v[166:169], v[62:65]
	v_mfma_f32_16x16x32_bf16 v[58:61], v[122:125], v[166:169], v[58:61]
	v_mfma_f32_16x16x32_bf16 v[42:45], v[122:125], v[174:177], v[42:45]
	v_mfma_f32_16x16x32_bf16 v[46:49], v[102:105], v[174:177], v[46:49]
	v_mfma_f32_16x16x32_bf16 v[30:33], v[102:105], v[182:185], v[30:33]
	v_mfma_f32_16x16x32_bf16 v[26:29], v[122:125], v[182:185], v[26:29]
	v_mfma_f32_16x16x32_bf16 v[10:13], v[122:125], v[190:193], v[10:13]
	v_mfma_f32_16x16x32_bf16 v[14:17], v[102:105], v[190:193], v[14:17]
	v_mfma_f32_16x16x32_bf16 v[54:57], v[130:133], v[162:165], v[54:57]
	v_mfma_f32_16x16x32_bf16 v[50:53], v[146:149], v[162:165], v[50:53]
	v_mfma_f32_16x16x32_bf16 v[34:37], v[146:149], v[170:173], v[34:37]
	v_mfma_f32_16x16x32_bf16 v[38:41], v[130:133], v[170:173], v[38:41]
	v_mfma_f32_16x16x32_bf16 v[22:25], v[130:133], v[178:181], v[22:25]
	v_mfma_f32_16x16x32_bf16 v[18:21], v[146:149], v[178:181], v[18:21]
	v_mfma_f32_16x16x32_bf16 v[2:5], v[146:149], v[186:189], v[2:5]
	v_mfma_f32_16x16x32_bf16 v[6:9], v[130:133], v[186:189], v[6:9]
	v_mfma_f32_16x16x32_bf16 v[54:57], v[138:141], v[166:169], v[54:57]
	v_mfma_f32_16x16x32_bf16 v[50:53], v[154:157], v[166:169], v[50:53]
	v_mfma_f32_16x16x32_bf16 v[34:37], v[154:157], v[174:177], v[34:37]
	v_mfma_f32_16x16x32_bf16 v[38:41], v[138:141], v[174:177], v[38:41]
	v_mfma_f32_16x16x32_bf16 v[22:25], v[138:141], v[182:185], v[22:25]
	v_mfma_f32_16x16x32_bf16 v[18:21], v[154:157], v[182:185], v[18:21]
	v_mfma_f32_16x16x32_bf16 v[2:5], v[154:157], v[190:193], v[2:5]
	v_mfma_f32_16x16x32_bf16 v[6:9], v[138:141], v[190:193], v[6:9]
	s_barrier
	s_add_u32 s6, s6, s98
	s_addc_u32 s7, s7, 0
	s_add_u32 s6, s6, s98
	s_addc_u32 s7, s7, 0
	s_add_u32 s67, s67, s98
	s_addc_u32 s85, s85, 0
	s_add_u32 s67, s67, s98
	s_addc_u32 s85, s85, 0
	s_cmp_ge_u32 vcc_lo, s69
	s_mov_b32 s8, vcc_lo
	s_cbranch_scc0 .LBB0_175
	s_branch .Lpeelx175
; #define PG8_STAGE(bufoff, gbase, voff) do { _Pragma("unroll") for (int _i = 0; _i < 2; ++_i) \
;         __builtin_amdgcn_global_load_lds((const unsigned*)((const char*)(gbase) + (voff)[_i]), (PG8_LAS unsigned*)(lds + (bufoff) + ldsw + _i * 8192), 16, 0, 0); } while (0)
; #define PG8_LDA(dst, b, h) do { _Pragma("unroll") for (int m = 0; m < 4; ++m) _Pragma("unroll") for (int k = 0; k < 2; ++k) dst[m][k] = *(const PG8_LAS bf16x8*)(lds + PG8_SA(b, h) + aoff + m * 2048 + k * 1024); } while (0)
; #define PG8_LDB(dst, b, h) do { _Pragma("unroll") for (int n = 0; n < 2; ++n) _Pragma("unroll") for (int k = 0; k < 2; ++k) dst[n][k] = *(const PG8_LAS bf16x8*)(lds + PG8_SB(b, h) + boff + n * 2048 + k * 1024); } while (0)
; #define PG8_MMA(ai, bj, At, Bt) do { __builtin_amdgcn_s_setprio(1); _Pragma("unroll") for (int m = 0; m < 4; ++m) _Pragma("unroll") for (int n = 0; n < 2; ++n) _Pragma("unroll") for (int k = 0; k < 2; ++k) \
;         acc[ai][bj][m][n] = mma16<Epi::I8>(Bt[n][k], At[m][k], acc[ai][bj][m][n]); __builtin_amdgcn_s_setprio(0); } while (0)
; #define PG8_WAIT_V(n) asm volatile("s_waitcnt vmcnt(" #n ")" ::: "memory")
; #define PG8_WAIT_L(n) asm volatile("s_waitcnt lgkmcnt(" #n ")" ::: "memory")
; #define PG8_BAR __builtin_amdgcn_s_barrier()
; template <class Epi, class Sched, bool ALIGN_EPI = false, bool SP2 = false>
; __device__ __forceinline__ void gemm_phase(PG8_LAS unsigned char* lds, const Gemm g, const Sched& S, const Epi& E) {
;     ...
;             const bool last = (t == nt - 2);
;             const char* a1 = cA + (size_t)(t + 1) * kstep;
;             const char* a2 = last ? nA : cA + (size_t)(t + 2) * kstep; const char* b2 = last ? nB : cB + (size_t)(t + 2) * kstep;
;             const char* a3 = a2 + kstep; const char* b3 = b2 + kstep;
;             if (last && has_next) S.a_ready(nxt);
;             if constexpr (SP2) {
;             PG8_LDB(B0, 0, 0); PG8_LDB(B1, 0, 1); PG8_SCHED; PG8_LDA(At, 0, 0); PG8_STAGE(PG8_SA(1, 1), a1 + hstep, voffA);
;             PG8_WAIT_V(8); PG8_WAIT_L(0); PG8_BAR; PG8_MMA(0, 0, At, B0); PG8_MMA(0, 1, At, B1); PG8_BAR; PG8_SCHED;
;             PG8_LDA(At, 0, 1); PG8_STAGE(PG8_SB(0, 0), b2, voffB); PG8_STAGE(PG8_SB(0, 1), b2 + hstep, voffB); PG8_STAGE(PG8_SA(0, 0), a2, voffA);
;             PG8_WAIT_V(8); PG8_WAIT_L(0); PG8_BAR; PG8_MMA(1, 0, At, B0); PG8_MMA(1, 1, At, B1); PG8_BAR; PG8_SCHED;
.LBB0_175:
	s_add_i32 vcc_lo, s8, 2
	s_add_u32 s4, s6, s98
	s_addc_u32 s5, s7, 0
	s_add_i32 vcc_hi, 0, 0x10000
	s_cmp_eq_u32 s13, s8
	s_cselect_b32 s9, s1, s5
	s_cselect_b32 s8, s0, s4
	s_cselect_b32 s5, s97, s85
	s_cselect_b32 s4, s96, s67
	s_add_i32 s84, 0, 0x14000
	v_add_u32_e32 v122, vcc_hi, v248
	v_add_u32_e32 v154, s84, v248
	ds_read_b128 v[98:101], v122
	ds_read_b128 v[102:105], v122 offset:1024
	ds_read_b128 v[114:117], v122 offset:2048
	ds_read_b128 v[122:125], v122 offset:3072
	ds_read_b128 v[130:133], v154
	ds_read_b128 v[138:141], v154 offset:1024
	ds_read_b128 v[146:149], v154 offset:2048
	ds_read_b128 v[154:157], v154 offset:3072
	s_add_i32 m0, s81, 0xc000
	ds_read_b128 v[162:165], v249
	ds_read_b128 v[166:169], v249 offset:1024
	ds_read_b128 v[170:173], v249 offset:2048
	ds_read_b128 v[174:177], v249 offset:3072
	ds_read_b128 v[178:181], v249 offset:4096
	ds_read_b128 v[182:185], v249 offset:5120
	ds_read_b128 v[186:189], v249 offset:6144
	ds_read_b128 v[190:193], v249 offset:7168
	global_load_lds_dwordx4 v200, s[6:7]
	s_add_i32 m0, s81, 0xe000
	s_nop 0
	global_load_lds_dwordx4 v210, s[6:7]
	s_waitcnt vmcnt(8)
	s_waitcnt lgkmcnt(0)
	s_barrier
	s_waitcnt lgkmcnt(0)
	v_mfma_f32_16x16x32_bf16 v[158:161], v[98:101], v[162:165], v[158:161]
	v_mfma_f32_16x16x32_bf16 v[150:153], v[114:117], v[162:165], v[150:153]
	v_mfma_f32_16x16x32_bf16 v[118:121], v[114:117], v[170:173], v[118:121]
	v_mfma_f32_16x16x32_bf16 v[126:129], v[98:101], v[170:173], v[126:129]
	v_mfma_f32_16x16x32_bf16 v[94:97], v[98:101], v[178:181], v[94:97]
	v_mfma_f32_16x16x32_bf16 v[90:93], v[114:117], v[178:181], v[90:93]
	v_mfma_f32_16x16x32_bf16 v[74:77], v[114:117], v[186:189], v[74:77]
	v_mfma_f32_16x16x32_bf16 v[78:81], v[98:101], v[186:189], v[78:81]
	v_mfma_f32_16x16x32_bf16 v[158:161], v[102:105], v[166:169], v[158:161]
	v_mfma_f32_16x16x32_bf16 v[150:153], v[122:125], v[166:169], v[150:153]
	v_mfma_f32_16x16x32_bf16 v[118:121], v[122:125], v[174:177], v[118:121]
	v_mfma_f32_16x16x32_bf16 v[126:129], v[102:105], v[174:177], v[126:129]
	v_mfma_f32_16x16x32_bf16 v[94:97], v[102:105], v[182:185], v[94:97]
	v_mfma_f32_16x16x32_bf16 v[90:93], v[122:125], v[182:185], v[90:93]
	v_mfma_f32_16x16x32_bf16 v[74:77], v[122:125], v[190:193], v[74:77]
	v_mfma_f32_16x16x32_bf16 v[78:81], v[102:105], v[190:193], v[78:81]
	v_mfma_f32_16x16x32_bf16 v[142:145], v[130:133], v[162:165], v[142:145]
	v_mfma_f32_16x16x32_bf16 v[134:137], v[146:149], v[162:165], v[134:137]
	v_mfma_f32_16x16x32_bf16 v[106:109], v[146:149], v[170:173], v[106:109]
	v_mfma_f32_16x16x32_bf16 v[110:113], v[130:133], v[170:173], v[110:113]
	v_mfma_f32_16x16x32_bf16 v[86:89], v[130:133], v[178:181], v[86:89]
	v_mfma_f32_16x16x32_bf16 v[82:85], v[146:149], v[178:181], v[82:85]
	v_mfma_f32_16x16x32_bf16 v[66:69], v[146:149], v[186:189], v[66:69]
	v_mfma_f32_16x16x32_bf16 v[70:73], v[130:133], v[186:189], v[70:73]
	v_mfma_f32_16x16x32_bf16 v[142:145], v[138:141], v[166:169], v[142:145]
	v_mfma_f32_16x16x32_bf16 v[134:137], v[154:157], v[166:169], v[134:137]
	v_mfma_f32_16x16x32_bf16 v[106:109], v[154:157], v[174:177], v[106:109]
	v_mfma_f32_16x16x32_bf16 v[110:113], v[138:141], v[174:177], v[110:113]
	v_mfma_f32_16x16x32_bf16 v[86:89], v[138:141], v[182:185], v[86:89]
	v_mfma_f32_16x16x32_bf16 v[82:85], v[154:157], v[182:185], v[82:85]
	v_mfma_f32_16x16x32_bf16 v[66:69], v[154:157], v[190:193], v[66:69]
	v_mfma_f32_16x16x32_bf16 v[70:73], v[138:141], v[190:193], v[70:73]
	s_barrier
	s_add_i32 vcc_hi, vcc_hi, s80
	s_mov_b64 s[92:93], s[4:5]
	s_mov_b32 m0, vcc_hi
	ds_read_b128 v[162:165], v249 offset:16384
	ds_read_b128 v[166:169], v249 offset:17408
	ds_read_b128 v[170:173], v249 offset:18432
	ds_read_b128 v[174:177], v249 offset:19456
	ds_read_b128 v[178:181], v249 offset:20480
	ds_read_b128 v[182:185], v249 offset:21504
	ds_read_b128 v[186:189], v249 offset:22528
	ds_read_b128 v[190:193], v249 offset:23552
	global_load_lds_dwordx4 v0, s[4:5]
	s_add_i32 m0, vcc_hi, 0x2000
	s_add_i32 s84, s84, s80
	global_load_lds_dwordx4 v198, s[4:5]
	s_add_u32 s4, s4, s100
	s_addc_u32 s5, s5, 0
	s_mov_b32 m0, s84
	s_nop 0
	global_load_lds_dwordx4 v0, s[4:5]
	s_add_i32 m0, s84, 0x2000
	s_nop 0
	global_load_lds_dwordx4 v198, s[4:5]
	s_mov_b32 m0, s81
	s_nop 0
	global_load_lds_dwordx4 v194, s[8:9]
	s_mov_b32 m0, s70
	s_nop 0
	global_load_lds_dwordx4 v196, s[8:9]
	s_waitcnt vmcnt(8)
	s_waitcnt lgkmcnt(0)
	s_barrier
	s_waitcnt lgkmcnt(0)
	v_mfma_f32_16x16x32_bf16 v[62:65], v[98:101], v[162:165], v[62:65]
	v_mfma_f32_16x16x32_bf16 v[58:61], v[114:117], v[162:165], v[58:61]
	v_mfma_f32_16x16x32_bf16 v[42:45], v[114:117], v[170:173], v[42:45]
	v_mfma_f32_16x16x32_bf16 v[46:49], v[98:101], v[170:173], v[46:49]
	v_mfma_f32_16x16x32_bf16 v[30:33], v[98:101], v[178:181], v[30:33]
	v_mfma_f32_16x16x32_bf16 v[26:29], v[114:117], v[178:181], v[26:29]
	v_mfma_f32_16x16x32_bf16 v[10:13], v[114:117], v[186:189], v[10:13]
	v_mfma_f32_16x16x32_bf16 v[14:17], v[98:101], v[186:189], v[14:17]
	v_mfma_f32_16x16x32_bf16 v[62:65], v[102:105], v[166:169], v[62:65]
	v_mfma_f32_16x16x32_bf16 v[58:61], v[122:125], v[166:169], v[58:61]
	v_mfma_f32_16x16x32_bf16 v[42:45], v[122:125], v[174:177], v[42:45]
	v_mfma_f32_16x16x32_bf16 v[46:49], v[102:105], v[174:177], v[46:49]
	v_mfma_f32_16x16x32_bf16 v[30:33], v[102:105], v[182:185], v[30:33]
	v_mfma_f32_16x16x32_bf16 v[26:29], v[122:125], v[182:185], v[26:29]
	v_mfma_f32_16x16x32_bf16 v[10:13], v[122:125], v[190:193], v[10:13]
	v_mfma_f32_16x16x32_bf16 v[14:17], v[102:105], v[190:193], v[14:17]
	v_mfma_f32_16x16x32_bf16 v[54:57], v[130:133], v[162:165], v[54:57]
	v_mfma_f32_16x16x32_bf16 v[50:53], v[146:149], v[162:165], v[50:53]
	v_mfma_f32_16x16x32_bf16 v[34:37], v[146:149], v[170:173], v[34:37]
	v_mfma_f32_16x16x32_bf16 v[38:41], v[130:133], v[170:173], v[38:41]
	v_mfma_f32_16x16x32_bf16 v[22:25], v[130:133], v[178:181], v[22:25]
	v_mfma_f32_16x16x32_bf16 v[18:21], v[146:149], v[178:181], v[18:21]
	v_mfma_f32_16x16x32_bf16 v[2:5], v[146:149], v[186:189], v[2:5]
	v_mfma_f32_16x16x32_bf16 v[6:9], v[130:133], v[186:189], v[6:9]
	v_mfma_f32_16x16x32_bf16 v[54:57], v[138:141], v[166:169], v[54:57]
	v_mfma_f32_16x16x32_bf16 v[50:53], v[154:157], v[166:169], v[50:53]
	v_mfma_f32_16x16x32_bf16 v[34:37], v[154:157], v[174:177], v[34:37]
	v_mfma_f32_16x16x32_bf16 v[38:41], v[138:141], v[174:177], v[38:41]
	v_mfma_f32_16x16x32_bf16 v[22:25], v[138:141], v[182:185], v[22:25]
	v_mfma_f32_16x16x32_bf16 v[18:21], v[154:157], v[182:185], v[18:21]
	v_mfma_f32_16x16x32_bf16 v[2:5], v[154:157], v[190:193], v[2:5]
	v_mfma_f32_16x16x32_bf16 v[6:9], v[138:141], v[190:193], v[6:9]
	s_barrier
; #define PG8_STAGE(bufoff, gbase, voff) do { _Pragma("unroll") for (int _i = 0; _i < 2; ++_i) \
;         __builtin_amdgcn_global_load_lds((const unsigned*)((const char*)(gbase) + (voff)[_i]), (PG8_LAS unsigned*)(lds + (bufoff) + ldsw + _i * 8192), 16, 0, 0); } while (0)
; #define PG8_LDA(dst, b, h) do { _Pragma("unroll") for (int m = 0; m < 4; ++m) _Pragma("unroll") for (int k = 0; k < 2; ++k) dst[m][k] = *(const PG8_LAS bf16x8*)(lds + PG8_SA(b, h) + aoff + m * 2048 + k * 1024); } while (0)
; #define PG8_LDB(dst, b, h) do { _Pragma("unroll") for (int n = 0; n < 2; ++n) _Pragma("unroll") for (int k = 0; k < 2; ++k) dst[n][k] = *(const PG8_LAS bf16x8*)(lds + PG8_SB(b, h) + boff + n * 2048 + k * 1024); } while (0)
; #define PG8_MMA(ai, bj, At, Bt) do { __builtin_amdgcn_s_setprio(1); _Pragma("unroll") for (int m = 0; m < 4; ++m) _Pragma("unroll") for (int n = 0; n < 2; ++n) _Pragma("unroll") for (int k = 0; k < 2; ++k) \
;         acc[ai][bj][m][n] = mma16<Epi::I8>(Bt[n][k], At[m][k], acc[ai][bj][m][n]); __builtin_amdgcn_s_setprio(0); } while (0)
; #define PG8_WAIT_V(n) asm volatile("s_waitcnt vmcnt(" #n ")" ::: "memory")
; #define PG8_WAIT_L(n) asm volatile("s_waitcnt lgkmcnt(" #n ")" ::: "memory")
; #define PG8_BAR __builtin_amdgcn_s_barrier()
; #define PG8_SCHED __builtin_amdgcn_sched_barrier(0)
; template <class Epi, class Sched, bool ALIGN_EPI = false, bool SP2 = false>
; __device__ __forceinline__ void gemm_phase(PG8_LAS unsigned char* lds, const Gemm g, const Sched& S, const Epi& E) {
;     ...
;             PG8_LDB(B0, 1, 0); PG8_LDB(B1, 1, 1); PG8_SCHED; PG8_LDA(At, 1, 0); PG8_STAGE(PG8_SA(0, 1), a2 + hstep, voffA);
;             PG8_WAIT_V(8); PG8_WAIT_L(0); PG8_BAR; PG8_MMA(0, 0, At, B0); PG8_MMA(0, 1, At, B1); PG8_BAR; PG8_SCHED;
;             PG8_LDA(At, 1, 1); PG8_STAGE(PG8_SB(1, 0), b3, voffB); PG8_STAGE(PG8_SB(1, 1), b3 + hstep, voffB); PG8_STAGE(PG8_SA(1, 0), a3, voffA);
;             PG8_WAIT_V(8); PG8_WAIT_L(0); PG8_BAR; PG8_MMA(1, 0, At, B0); PG8_MMA(1, 1, At, B1); PG8_BAR; PG8_SCHED;
;     ...
;         if constexpr (ALIGN_EPI) { if (wr == 0) PG8_BAR; }
	s_add_i32 s84, 0, 0x18000
	s_add_i32 vcc_hi, 0, 0x1c000
	v_add_u32_e32 v122, s84, v248
	v_add_u32_e32 v154, vcc_hi, v248
	ds_read_b128 v[98:101], v122
	ds_read_b128 v[102:105], v122 offset:1024
	ds_read_b128 v[114:117], v122 offset:2048
	ds_read_b128 v[122:125], v122 offset:3072
	ds_read_b128 v[130:133], v154
	ds_read_b128 v[138:141], v154 offset:1024
	ds_read_b128 v[146:149], v154 offset:2048
	ds_read_b128 v[154:157], v154 offset:3072
	s_add_u32 s4, s8, s100
	s_addc_u32 s5, s9, 0
	s_mov_b32 m0, s71
	ds_read_b128 v[162:165], v249 offset:32768
	ds_read_b128 v[166:169], v249 offset:33792
	ds_read_b128 v[170:173], v249 offset:34816
	ds_read_b128 v[174:177], v249 offset:35840
	ds_read_b128 v[178:181], v249 offset:36864
	ds_read_b128 v[182:185], v249 offset:37888
	ds_read_b128 v[186:189], v249 offset:38912
	ds_read_b128 v[190:193], v249 offset:39936
	global_load_lds_dwordx4 v194, s[4:5]
	s_mov_b32 m0, s12
	s_nop 0
	global_load_lds_dwordx4 v196, s[4:5]
	s_waitcnt vmcnt(8)
	s_waitcnt lgkmcnt(0)
	s_barrier
	s_waitcnt lgkmcnt(0)
	v_mfma_f32_16x16x32_bf16 v[158:161], v[98:101], v[162:165], v[158:161]
	v_mfma_f32_16x16x32_bf16 v[150:153], v[114:117], v[162:165], v[150:153]
	v_mfma_f32_16x16x32_bf16 v[118:121], v[114:117], v[170:173], v[118:121]
	v_mfma_f32_16x16x32_bf16 v[126:129], v[98:101], v[170:173], v[126:129]
	v_mfma_f32_16x16x32_bf16 v[94:97], v[98:101], v[178:181], v[94:97]
	v_mfma_f32_16x16x32_bf16 v[90:93], v[114:117], v[178:181], v[90:93]
	v_mfma_f32_16x16x32_bf16 v[74:77], v[114:117], v[186:189], v[74:77]
	v_mfma_f32_16x16x32_bf16 v[78:81], v[98:101], v[186:189], v[78:81]
	v_mfma_f32_16x16x32_bf16 v[158:161], v[102:105], v[166:169], v[158:161]
	v_mfma_f32_16x16x32_bf16 v[150:153], v[122:125], v[166:169], v[150:153]
	v_mfma_f32_16x16x32_bf16 v[118:121], v[122:125], v[174:177], v[118:121]
	v_mfma_f32_16x16x32_bf16 v[126:129], v[102:105], v[174:177], v[126:129]
	v_mfma_f32_16x16x32_bf16 v[94:97], v[102:105], v[182:185], v[94:97]
	v_mfma_f32_16x16x32_bf16 v[90:93], v[122:125], v[182:185], v[90:93]
	v_mfma_f32_16x16x32_bf16 v[74:77], v[122:125], v[190:193], v[74:77]
	v_mfma_f32_16x16x32_bf16 v[78:81], v[102:105], v[190:193], v[78:81]
	v_mfma_f32_16x16x32_bf16 v[142:145], v[130:133], v[162:165], v[142:145]
	v_mfma_f32_16x16x32_bf16 v[134:137], v[146:149], v[162:165], v[134:137]
	v_mfma_f32_16x16x32_bf16 v[106:109], v[146:149], v[170:173], v[106:109]
	v_mfma_f32_16x16x32_bf16 v[110:113], v[130:133], v[170:173], v[110:113]
	v_mfma_f32_16x16x32_bf16 v[86:89], v[130:133], v[178:181], v[86:89]
	v_mfma_f32_16x16x32_bf16 v[82:85], v[146:149], v[178:181], v[82:85]
	v_mfma_f32_16x16x32_bf16 v[66:69], v[146:149], v[186:189], v[66:69]
	v_mfma_f32_16x16x32_bf16 v[70:73], v[130:133], v[186:189], v[70:73]
	v_mfma_f32_16x16x32_bf16 v[142:145], v[138:141], v[166:169], v[142:145]
	v_mfma_f32_16x16x32_bf16 v[134:137], v[154:157], v[166:169], v[134:137]
	v_mfma_f32_16x16x32_bf16 v[106:109], v[154:157], v[174:177], v[106:109]
	v_mfma_f32_16x16x32_bf16 v[110:113], v[138:141], v[174:177], v[110:113]
	v_mfma_f32_16x16x32_bf16 v[86:89], v[138:141], v[182:185], v[86:89]
	v_mfma_f32_16x16x32_bf16 v[82:85], v[154:157], v[182:185], v[82:85]
	v_mfma_f32_16x16x32_bf16 v[66:69], v[154:157], v[190:193], v[66:69]
	v_mfma_f32_16x16x32_bf16 v[70:73], v[138:141], v[190:193], v[70:73]
	s_barrier
	s_add_u32 s4, s92, s98
	s_addc_u32 s5, s93, 0
	s_add_i32 m0, s84, s80
	ds_read_b128 v[162:165], v249 offset:49152
	ds_read_b128 v[166:169], v249 offset:50176
	ds_read_b128 v[170:173], v249 offset:51200
	ds_read_b128 v[174:177], v249 offset:52224
	ds_read_b128 v[178:181], v249 offset:53248
	ds_read_b128 v[182:185], v249 offset:54272
	ds_read_b128 v[186:189], v249 offset:55296
	ds_read_b128 v[190:193], v249 offset:56320
	global_load_lds_dwordx4 v0, s[4:5]
	s_add_i32 m0, s84, s80
	s_add_i32 m0, m0, 0x2000
	s_nop 0
	global_load_lds_dwordx4 v198, s[4:5]
	s_add_u32 s4, s4, s100
	s_addc_u32 s5, s5, 0
	s_add_i32 m0, vcc_hi, s80
	s_nop 0
	global_load_lds_dwordx4 v0, s[4:5]
	s_add_i32 m0, vcc_hi, s80
	s_add_i32 m0, m0, 0x2000
	s_nop 0
	global_load_lds_dwordx4 v198, s[4:5]
	s_add_u32 s4, s8, s98
	s_addc_u32 s5, s9, 0
	s_mov_b32 m0, s10
	s_nop 0
	global_load_lds_dwordx4 v194, s[4:5]
	s_mov_b32 m0, s11
	s_nop 0
	global_load_lds_dwordx4 v196, s[4:5]
	s_waitcnt vmcnt(8)
	s_waitcnt lgkmcnt(0)
	s_barrier
	s_waitcnt lgkmcnt(0)
	v_mfma_f32_16x16x32_bf16 v[62:65], v[98:101], v[162:165], v[62:65]
	v_mfma_f32_16x16x32_bf16 v[58:61], v[114:117], v[162:165], v[58:61]
	v_mfma_f32_16x16x32_bf16 v[42:45], v[114:117], v[170:173], v[42:45]
	v_mfma_f32_16x16x32_bf16 v[46:49], v[98:101], v[170:173], v[46:49]
	v_mfma_f32_16x16x32_bf16 v[30:33], v[98:101], v[178:181], v[30:33]
	v_mfma_f32_16x16x32_bf16 v[26:29], v[114:117], v[178:181], v[26:29]
	v_mfma_f32_16x16x32_bf16 v[10:13], v[114:117], v[186:189], v[10:13]
	v_mfma_f32_16x16x32_bf16 v[14:17], v[98:101], v[186:189], v[14:17]
	v_mfma_f32_16x16x32_bf16 v[62:65], v[102:105], v[166:169], v[62:65]
	v_mfma_f32_16x16x32_bf16 v[58:61], v[122:125], v[166:169], v[58:61]
	v_mfma_f32_16x16x32_bf16 v[42:45], v[122:125], v[174:177], v[42:45]
	v_mfma_f32_16x16x32_bf16 v[46:49], v[102:105], v[174:177], v[46:49]
	v_mfma_f32_16x16x32_bf16 v[30:33], v[102:105], v[182:185], v[30:33]
	v_mfma_f32_16x16x32_bf16 v[26:29], v[122:125], v[182:185], v[26:29]
	v_mfma_f32_16x16x32_bf16 v[10:13], v[122:125], v[190:193], v[10:13]
	v_mfma_f32_16x16x32_bf16 v[14:17], v[102:105], v[190:193], v[14:17]
	v_mfma_f32_16x16x32_bf16 v[54:57], v[130:133], v[162:165], v[54:57]
	v_mfma_f32_16x16x32_bf16 v[50:53], v[146:149], v[162:165], v[50:53]
	v_mfma_f32_16x16x32_bf16 v[34:37], v[146:149], v[170:173], v[34:37]
	v_mfma_f32_16x16x32_bf16 v[38:41], v[130:133], v[170:173], v[38:41]
	v_mfma_f32_16x16x32_bf16 v[22:25], v[130:133], v[178:181], v[22:25]
	v_mfma_f32_16x16x32_bf16 v[18:21], v[146:149], v[178:181], v[18:21]
	v_mfma_f32_16x16x32_bf16 v[2:5], v[146:149], v[186:189], v[2:5]
	v_mfma_f32_16x16x32_bf16 v[6:9], v[130:133], v[186:189], v[6:9]
	v_mfma_f32_16x16x32_bf16 v[54:57], v[138:141], v[166:169], v[54:57]
	v_mfma_f32_16x16x32_bf16 v[50:53], v[154:157], v[166:169], v[50:53]
	v_mfma_f32_16x16x32_bf16 v[34:37], v[154:157], v[174:177], v[34:37]
	v_mfma_f32_16x16x32_bf16 v[38:41], v[138:141], v[174:177], v[38:41]
	v_mfma_f32_16x16x32_bf16 v[22:25], v[138:141], v[182:185], v[22:25]
	v_mfma_f32_16x16x32_bf16 v[18:21], v[154:157], v[182:185], v[18:21]
	v_mfma_f32_16x16x32_bf16 v[2:5], v[154:157], v[190:193], v[2:5]
	v_mfma_f32_16x16x32_bf16 v[6:9], v[138:141], v[190:193], v[6:9]
	s_barrier
	s_add_u32 s6, s6, s98
	s_addc_u32 s7, s7, 0
	s_add_u32 s6, s6, s98
	s_addc_u32 s7, s7, 0
	s_add_u32 s67, s67, s98
	s_addc_u32 s85, s85, 0
	s_add_u32 s67, s67, s98
	s_addc_u32 s85, s85, 0
	s_cmp_ge_u32 vcc_lo, s69
	s_mov_b32 s8, vcc_lo
	s_cbranch_scc0 .LBB0_175
.Lpeelx175:
	s_movk_i32 s92, 0x80
	s_mov_b32 s93, 0
	v_mov_b32_e32 v232, 0x8800
	v_mov_b32_e32 v231, 0x2000
	v_mov_b32_e32 v202, 1
	s_and_b64 vcc, exec, s[46:47]
	s_cbranch_vccz .LBB0_178
	s_barrier
